# attention priorities: MFMA sections prio 2 in all waves, skew-wave softmax prio 1, non-skew softmax prio 0 (on top of ds_read_b64 split)
# speedup vs baseline: 1.0007x; 1.0007x over previous
.LBB0_494:
	s_setprio 2
	v_add3_u32 v96, v166, s39, v164
	s_waitcnt vmcnt(1)
	v_add_u32_e32 v112, 0x2000, v96
	v_add_u32_e32 v113, 0x3000, v96
	v_add_u32_e32 v114, 0x4000, v96
	v_add_u32_e32 v115, 0x5000, v96
	ds_read_b64 v[80:81], v112 offset:1024
	ds_read_b64 v[82:83], v112 offset:1040
	ds_read_b64 v[88:89], v113 offset:1280
	ds_read_b64 v[90:91], v113 offset:1296
	ds_read_b64 v[92:93], v114 offset:1536
	ds_read_b64 v[94:95], v114 offset:1552
	ds_read_b64 v[96:97], v115 offset:1792
	ds_read_b64 v[98:99], v115 offset:1808
	ds_read_b64 v[84:85], v112 offset:1056
	ds_read_b64 v[86:87], v112 offset:1072
	ds_read_b64 v[100:101], v113 offset:1312
	ds_read_b64 v[102:103], v113 offset:1328
	ds_read_b64 v[104:105], v114 offset:1568
	ds_read_b64 v[106:107], v114 offset:1584
	ds_read_b64 v[108:109], v115 offset:1824
	ds_read_b64 v[110:111], v115 offset:1840
	s_waitcnt lgkmcnt(14)
	v_mfma_f32_32x32x16_bf16 v[0:15], v[80:83], v[76:79], v[0:15]
	s_waitcnt lgkmcnt(12)
	v_mfma_f32_32x32x16_bf16 v[48:63], v[88:91], v[76:79], v[48:63]
	s_waitcnt lgkmcnt(10)
	v_mfma_f32_32x32x16_bf16 v[32:47], v[92:95], v[76:79], v[32:47]
	s_waitcnt lgkmcnt(8)
	v_mfma_f32_32x32x16_bf16 v[16:31], v[96:99], v[76:79], v[16:31]
	s_waitcnt lgkmcnt(6)
	v_mfma_f32_32x32x16_bf16 v[0:15], v[84:87], v[72:75], v[0:15]
	s_waitcnt lgkmcnt(4)
	v_mfma_f32_32x32x16_bf16 v[48:63], v[100:103], v[72:75], v[48:63]
	s_waitcnt lgkmcnt(2)
	v_mfma_f32_32x32x16_bf16 v[32:47], v[104:107], v[72:75], v[32:47]
	s_waitcnt lgkmcnt(0)
	v_mfma_f32_32x32x16_bf16 v[16:31], v[108:111], v[72:75], v[16:31]
	ds_read_b64 v[72:73], v112 offset:1088
	ds_read_b64 v[74:75], v112 offset:1104
	ds_read_b64 v[80:81], v113 offset:1344
	ds_read_b64 v[82:83], v113 offset:1360
	ds_read_b64 v[84:85], v114 offset:1600
	ds_read_b64 v[86:87], v114 offset:1616
	ds_read_b64 v[88:89], v115 offset:1856
	ds_read_b64 v[90:91], v115 offset:1872
	ds_read_b64 v[76:77], v112 offset:1120
	ds_read_b64 v[78:79], v112 offset:1136
	ds_read_b64 v[92:93], v113 offset:1376
	ds_read_b64 v[94:95], v113 offset:1392
	ds_read_b64 v[96:97], v114 offset:1632
	ds_read_b64 v[98:99], v114 offset:1648
	ds_read_b64 v[100:101], v115 offset:1888
	ds_read_b64 v[102:103], v115 offset:1904
	s_waitcnt lgkmcnt(14)
	v_mfma_f32_32x32x16_bf16 v[0:15], v[72:75], v[68:71], v[0:15]
	s_waitcnt lgkmcnt(12)
	v_mfma_f32_32x32x16_bf16 v[48:63], v[80:83], v[68:71], v[48:63]
	s_waitcnt lgkmcnt(10)
	v_mfma_f32_32x32x16_bf16 v[32:47], v[84:87], v[68:71], v[32:47]
	s_waitcnt lgkmcnt(8)
	v_mfma_f32_32x32x16_bf16 v[16:31], v[88:91], v[68:71], v[16:31]
	s_waitcnt lgkmcnt(6)
	v_mfma_f32_32x32x16_bf16 v[0:15], v[76:79], v[64:67], v[0:15]
	s_waitcnt lgkmcnt(4)
	v_mfma_f32_32x32x16_bf16 v[48:63], v[92:95], v[64:67], v[48:63]
	s_waitcnt lgkmcnt(2)
	v_mfma_f32_32x32x16_bf16 v[32:47], v[96:99], v[64:67], v[32:47]
	s_waitcnt lgkmcnt(0)
	v_mfma_f32_32x32x16_bf16 v[16:31], v[100:103], v[64:67], v[16:31]
	s_setprio 0

.LBB0_502:
	v_fma_f32 v80, v80, s33, -v172
	v_exp_f32_e32 v80, v80
	v_fma_f32 v81, v81, s33, -v172
	v_exp_f32_e32 v81, v81
	v_fma_f32 v82, v82, s33, -v172
	v_exp_f32_e32 v82, v82
	v_fma_f32 v83, v83, s33, -v172
	v_exp_f32_e32 v83, v83
	v_fma_f32 v84, v84, s33, -v172
	v_add_f32_e32 v173, 0, v80
	v_exp_f32_e32 v84, v84
	v_fma_f32 v85, v85, s33, -v172
	v_add_f32_e32 v173, v81, v173
	v_exp_f32_e32 v85, v85
	v_fma_f32 v86, v86, s33, -v172
	v_add_f32_e32 v173, v82, v173
	v_exp_f32_e32 v86, v86
	v_fma_f32 v87, v87, s33, -v172
	v_add_f32_e32 v173, v83, v173
	v_exp_f32_e32 v87, v87
	v_fma_f32 v88, v88, s33, -v172
	v_add_f32_e32 v173, v84, v173
	v_exp_f32_e32 v88, v88
	v_fma_f32 v89, v89, s33, -v172
	v_add_f32_e32 v173, v85, v173
	v_exp_f32_e32 v89, v89
	v_fma_f32 v90, v90, s33, -v172
	v_add_f32_e32 v173, v86, v173
	v_exp_f32_e32 v90, v90
	v_fma_f32 v91, v91, s33, -v172
	v_add_f32_e32 v173, v87, v173
	v_exp_f32_e32 v91, v91
	v_fma_f32 v92, v92, s33, -v172
	v_add_f32_e32 v173, v88, v173
	v_exp_f32_e32 v92, v92
	v_fma_f32 v93, v93, s33, -v172
	v_add_f32_e32 v173, v89, v173
	v_exp_f32_e32 v93, v93
	v_fma_f32 v94, v94, s33, -v172
	v_add_f32_e32 v173, v90, v173
	v_exp_f32_e32 v94, v94
	v_fma_f32 v95, v95, s33, -v172
	v_add_f32_e32 v173, v91, v173
	v_exp_f32_e32 v95, v95
	v_fma_f32 v64, v64, s33, -v172
	v_add_f32_e32 v173, v92, v173
	v_exp_f32_e32 v174, v64
	v_fma_f32 v64, v65, s33, -v172
	v_add_f32_e32 v173, v93, v173
	v_exp_f32_e32 v175, v64
	v_fma_f32 v64, v66, s33, -v172
	v_add_f32_e32 v173, v94, v173
	v_exp_f32_e32 v176, v64
	v_fma_f32 v64, v67, s33, -v172
	v_add_f32_e32 v173, v95, v173
	v_exp_f32_e32 v177, v64
	v_fma_f32 v65, v68, s33, -v172
	v_add_f32_e32 v64, v174, v173
	v_exp_f32_e32 v173, v65
	v_fma_f32 v65, v69, s33, -v172
	v_add_f32_e32 v64, v175, v64
	v_exp_f32_e32 v178, v65
	v_fma_f32 v65, v70, s33, -v172
	v_add_f32_e32 v64, v176, v64
	v_exp_f32_e32 v179, v65
	v_fma_f32 v65, v71, s33, -v172
	v_add_f32_e32 v64, v177, v64
	v_exp_f32_e32 v180, v65
	v_fma_f32 v65, v72, s33, -v172
	v_add_f32_e32 v64, v173, v64
	v_exp_f32_e32 v181, v65
	v_fma_f32 v65, v73, s33, -v172
	v_add_f32_e32 v64, v178, v64
	v_exp_f32_e32 v182, v65
	v_fma_f32 v65, v74, s33, -v172
	v_add_f32_e32 v64, v179, v64
	v_exp_f32_e32 v183, v65
	v_fma_f32 v65, v75, s33, -v172
	v_add_f32_e32 v64, v180, v64
	v_exp_f32_e32 v184, v65
	v_fma_f32 v65, v76, s33, -v172
	v_add_f32_e32 v64, v181, v64
	v_exp_f32_e32 v185, v65
	v_fma_f32 v65, v77, s33, -v172
	v_add_f32_e32 v64, v182, v64
	v_exp_f32_e32 v186, v65
	v_fma_f32 v65, v78, s33, -v172
	v_add_f32_e32 v64, v183, v64
	v_exp_f32_e32 v187, v65
	v_fma_f32 v65, v79, s33, -v172
	v_add_f32_e32 v64, v184, v64
	v_exp_f32_e32 v79, v65
	s_add_i32 s39, s12, 1
	v_add_f32_e32 v64, v185, v64
	s_cmp_lg_u32 s12, 2
	v_add_f32_e32 v64, v186, v64
	s_cselect_b32 s12, s39, 0
	v_add_f32_e32 v64, v187, v64
	v_add_f32_e32 v190, v79, v64
	v_cvt_pk_bf16_f32 v64, v80, v81
	v_cvt_pk_bf16_f32 v65, v82, v83
	v_cvt_pk_bf16_f32 v66, v84, v85
	v_cvt_pk_bf16_f32 v67, v86, v87
	v_cvt_pk_bf16_f32 v68, v88, v89
	v_cvt_pk_bf16_f32 v69, v90, v91
	v_cvt_pk_bf16_f32 v70, v92, v93
	v_cvt_pk_bf16_f32 v71, v94, v95
	v_cvt_pk_bf16_f32 v72, v174, v175
	v_cvt_pk_bf16_f32 v73, v176, v177
	v_cvt_pk_bf16_f32 v74, v173, v178
	v_cvt_pk_bf16_f32 v75, v179, v180
	v_cvt_pk_bf16_f32 v76, v181, v182
	v_cvt_pk_bf16_f32 v77, v183, v184
	v_cvt_pk_bf16_f32 v78, v185, v186
	v_cvt_pk_bf16_f32 v79, v187, v79
	s_mul_i32 s39, s12, 0x6800
	s_add_i32 s39, s39, 16
	v_add3_u32 v80, s39, v159, v160
	s_waitcnt vmcnt(2)
	ds_write_b128 v80, v[120:123]
	v_add_u32_e32 v80, s39, v161
	s_add_i32 s39, s13, 2
	s_min_i32 s39, s39, s6
	v_add_u32_e32 v81, 0x2400, v80
	v_add_u32_e32 v80, 0x4600, v80
	s_lshl_b32 s40, s39, 6
	s_waitcnt vmcnt(0)
	ds_write2_b64 v80, v[116:117], v[118:119] offset1:1
	v_add_u32_e32 v80, s40, v158
	ds_write2_b64 v81, v[112:113], v[114:115] offset1:1
	v_ashrrev_i32_e32 v81, 31, v80
	v_lshlrev_b64 v[80:81], 10, v[80:81]
	s_ashr_i32 s41, s40, 31
	v_lshl_add_u64 v[80:81], v[156:157], 0, v[80:81]
	s_lshl_b64 s[40:41], s[40:41], 1
	v_lshl_add_u64 v[82:83], v[152:153], 0, s[40:41]
	global_load_dwordx4 v[120:123], v[80:81], off
	v_lshl_add_u64 v[80:81], v[154:155], 0, s[40:41]
	global_load_dwordx4 v[112:115], v[82:83], off
	global_load_dwordx4 v[116:119], v[80:81], off
	s_setprio 2
	v_add3_u32 v173, s38, v136, v164
	v_add_u32_e32 v191, 0x2000, v173
	v_add_u32_e32 v192, 0x3000, v173
	v_add_u32_e32 v193, 0x4000, v173
	v_add_u32_e32 v173, 0x5000, v173
	ds_read_b64 v[80:81], v191 offset:1024
	ds_read_b64 v[82:83], v191 offset:1040
	ds_read_b64 v[88:89], v192 offset:1280
	ds_read_b64 v[90:91], v192 offset:1296
	ds_read_b64 v[92:93], v193 offset:1536
	ds_read_b64 v[94:95], v193 offset:1552
	ds_read_b64 v[174:175], v173 offset:1792
	ds_read_b64 v[176:177], v173 offset:1808
	ds_read_b64 v[84:85], v191 offset:1056
	ds_read_b64 v[86:87], v191 offset:1072
	ds_read_b64 v[178:179], v192 offset:1312
	ds_read_b64 v[180:181], v192 offset:1328
	ds_read_b64 v[182:183], v193 offset:1568
	ds_read_b64 v[184:185], v193 offset:1584
	ds_read_b64 v[186:187], v173 offset:1824
	ds_read_b64 v[188:189], v173 offset:1840
	s_waitcnt lgkmcnt(14)
	v_mfma_f32_32x32x16_bf16 v[0:15], v[80:83], v[64:67], v[0:15]
	s_waitcnt lgkmcnt(12)
	v_mfma_f32_32x32x16_bf16 v[48:63], v[88:91], v[64:67], v[48:63]
	s_waitcnt lgkmcnt(10)
	v_mfma_f32_32x32x16_bf16 v[32:47], v[92:95], v[64:67], v[32:47]
	s_waitcnt lgkmcnt(8)
	v_mfma_f32_32x32x16_bf16 v[16:31], v[174:177], v[64:67], v[16:31]
	s_waitcnt lgkmcnt(6)
	v_mfma_f32_32x32x16_bf16 v[0:15], v[84:87], v[68:71], v[0:15]
	s_waitcnt lgkmcnt(4)
	v_mfma_f32_32x32x16_bf16 v[48:63], v[178:181], v[68:71], v[48:63]
	s_waitcnt lgkmcnt(2)
	v_mfma_f32_32x32x16_bf16 v[32:47], v[182:185], v[68:71], v[32:47]
	s_waitcnt lgkmcnt(0)
	v_mfma_f32_32x32x16_bf16 v[16:31], v[186:189], v[68:71], v[16:31]
	ds_read_b64 v[64:65], v191 offset:1088
	ds_read_b64 v[66:67], v191 offset:1104
	ds_read_b64 v[80:81], v192 offset:1344
	ds_read_b64 v[82:83], v192 offset:1360
	ds_read_b64 v[84:85], v193 offset:1600
	ds_read_b64 v[86:87], v193 offset:1616
	ds_read_b64 v[88:89], v173 offset:1856
	ds_read_b64 v[90:91], v173 offset:1872
	ds_read_b64 v[68:69], v191 offset:1120
	ds_read_b64 v[70:71], v191 offset:1136
	ds_read_b64 v[92:93], v192 offset:1376
	ds_read_b64 v[94:95], v192 offset:1392
	ds_read_b64 v[174:175], v193 offset:1632
	ds_read_b64 v[176:177], v193 offset:1648
	ds_read_b64 v[178:179], v173 offset:1888
	ds_read_b64 v[180:181], v173 offset:1904
	s_waitcnt lgkmcnt(14)
	v_mfma_f32_32x32x16_bf16 v[0:15], v[64:67], v[72:75], v[0:15]
	s_waitcnt lgkmcnt(12)
	v_mfma_f32_32x32x16_bf16 v[48:63], v[80:83], v[72:75], v[48:63]
	s_waitcnt lgkmcnt(10)
	v_mfma_f32_32x32x16_bf16 v[32:47], v[84:87], v[72:75], v[32:47]
	s_waitcnt lgkmcnt(8)
	v_mfma_f32_32x32x16_bf16 v[16:31], v[88:91], v[72:75], v[16:31]
	s_waitcnt lgkmcnt(6)
	v_mfma_f32_32x32x16_bf16 v[0:15], v[68:71], v[76:79], v[0:15]
	s_waitcnt lgkmcnt(4)
	v_mfma_f32_32x32x16_bf16 v[48:63], v[92:95], v[76:79], v[48:63]
	s_waitcnt lgkmcnt(2)
	v_mfma_f32_32x32x16_bf16 v[32:47], v[174:177], v[76:79], v[32:47]
	s_waitcnt lgkmcnt(0)
	v_mfma_f32_32x32x16_bf16 v[16:31], v[178:181], v[76:79], v[16:31]
	v_add_f32_e32 v143, v143, v190
	s_setprio 0
	s_add_i32 s13, s13, 1
	s_cmp_eq_u32 s37, s13
	s_barrier
	s_cbranch_scc1 .LBB0_505
.LBB0_503:
	s_mul_i32 s38, s12, 0x6800
	s_add_i32 s38, s38, 16
	s_setprio 2
	v_add3_u32 v72, s38, v162, v163
	ds_read_b128 v[64:67], v72
	ds_read_b128 v[68:71], v72 offset:4608
	ds_read_b128 v[174:177], v72 offset:32
	ds_read_b128 v[178:181], v72 offset:4640
	ds_read_b128 v[182:185], v72 offset:64
	ds_read_b128 v[186:189], v72 offset:4672
	ds_read_b128 v[190:193], v72 offset:96
	ds_read_b128 v[194:197], v72 offset:4704
	s_waitcnt lgkmcnt(7)
	v_mfma_f32_32x32x16_bf16 v[80:95], v[64:67], v[108:111], 0
	s_waitcnt lgkmcnt(6)
	v_mfma_f32_32x32x16_bf16 v[64:79], v[68:71], v[108:111], 0
	s_waitcnt lgkmcnt(5)
	v_mfma_f32_32x32x16_bf16 v[80:95], v[174:177], v[96:99], v[80:95]
	s_waitcnt lgkmcnt(4)
	v_mfma_f32_32x32x16_bf16 v[64:79], v[178:181], v[96:99], v[64:79]
	s_waitcnt lgkmcnt(3)
	v_mfma_f32_32x32x16_bf16 v[80:95], v[182:185], v[100:103], v[80:95]
	s_waitcnt lgkmcnt(2)
	v_mfma_f32_32x32x16_bf16 v[64:79], v[186:189], v[100:103], v[64:79]
	s_waitcnt lgkmcnt(1)
	v_mfma_f32_32x32x16_bf16 v[80:95], v[190:193], v[104:107], v[80:95]
	s_waitcnt lgkmcnt(0)
	v_mfma_f32_32x32x16_bf16 v[64:79], v[194:197], v[104:107], v[64:79]
	s_setprio 0
	s_nop 8
	v_max_f32_e32 v173, v81, v81
	v_max_f32_e32 v174, v80, v80
	v_max_f32_e32 v173, v174, v173
	v_max3_f32 v173, v173, v82, v83
	v_max3_f32 v173, v173, v84, v85
	v_max3_f32 v173, v173, v86, v87
	v_max3_f32 v173, v173, v88, v89
	v_max3_f32 v173, v173, v90, v91
	v_max3_f32 v173, v173, v92, v93
	v_max3_f32 v173, v173, v94, v95
	v_max3_f32 v173, v173, v64, v65
	v_max3_f32 v173, v173, v66, v67
	v_max3_f32 v173, v173, v68, v69
	v_max3_f32 v173, v173, v70, v71
	v_max3_f32 v173, v173, v72, v73
	v_max3_f32 v173, v173, v74, v75
	v_max3_f32 v173, v173, v76, v77
	v_max3_f32 v173, v173, v78, v79
	v_mov_b32_e32 v174, v173
	s_nop 1
	v_permlane32_swap_b32_e32 v173, v174
	v_max_f32_e32 v174, v174, v174
	v_max_f32_e32 v173, v173, v173
	v_max_f32_e32 v173, v173, v174
	v_mul_f32_e32 v173, 0x3e38aa3b, v173
	v_add_f32_e32 v174, 0x41000000, v172
	v_cmp_gt_f32_e32 vcc, v173, v174
	s_cbranch_vccz .LBB0_502
	v_max_f32_e32 v173, v173, v173
	v_max_f32_e32 v174, v172, v172
	v_max_f32_e32 v173, v174, v173
	v_sub_f32_e32 v172, v172, v173
	v_exp_f32_e32 v172, v172
	s_nop 0
	v_pk_mul_f32 v[14:15], v[14:15], v[172:173] op_sel_hi:[1,0]
	v_pk_mul_f32 v[12:13], v[12:13], v[172:173] op_sel_hi:[1,0]
	v_pk_mul_f32 v[10:11], v[10:11], v[172:173] op_sel_hi:[1,0]
	v_pk_mul_f32 v[8:9], v[8:9], v[172:173] op_sel_hi:[1,0]
	v_pk_mul_f32 v[6:7], v[6:7], v[172:173] op_sel_hi:[1,0]
	v_pk_mul_f32 v[4:5], v[4:5], v[172:173] op_sel_hi:[1,0]
	v_pk_mul_f32 v[2:3], v[2:3], v[172:173] op_sel_hi:[1,0]
	v_pk_mul_f32 v[0:1], v[0:1], v[172:173] op_sel_hi:[1,0]
	v_pk_mul_f32 v[62:63], v[62:63], v[172:173] op_sel_hi:[1,0]
	v_pk_mul_f32 v[60:61], v[60:61], v[172:173] op_sel_hi:[1,0]
	v_pk_mul_f32 v[58:59], v[58:59], v[172:173] op_sel_hi:[1,0]
	v_pk_mul_f32 v[56:57], v[56:57], v[172:173] op_sel_hi:[1,0]
	v_pk_mul_f32 v[54:55], v[54:55], v[172:173] op_sel_hi:[1,0]
	v_pk_mul_f32 v[52:53], v[52:53], v[172:173] op_sel_hi:[1,0]
	v_pk_mul_f32 v[50:51], v[50:51], v[172:173] op_sel_hi:[1,0]
	v_pk_mul_f32 v[48:49], v[48:49], v[172:173] op_sel_hi:[1,0]
	v_pk_mul_f32 v[46:47], v[46:47], v[172:173] op_sel_hi:[1,0]
	v_pk_mul_f32 v[44:45], v[44:45], v[172:173] op_sel_hi:[1,0]
	v_pk_mul_f32 v[42:43], v[42:43], v[172:173] op_sel_hi:[1,0]
	v_pk_mul_f32 v[40:41], v[40:41], v[172:173] op_sel_hi:[1,0]
	v_pk_mul_f32 v[38:39], v[38:39], v[172:173] op_sel_hi:[1,0]
	v_pk_mul_f32 v[36:37], v[36:37], v[172:173] op_sel_hi:[1,0]
	v_pk_mul_f32 v[34:35], v[34:35], v[172:173] op_sel_hi:[1,0]
	v_pk_mul_f32 v[32:33], v[32:33], v[172:173] op_sel_hi:[1,0]
	v_pk_mul_f32 v[30:31], v[30:31], v[172:173] op_sel_hi:[1,0]
	v_pk_mul_f32 v[28:29], v[28:29], v[172:173] op_sel_hi:[1,0]
	v_pk_mul_f32 v[26:27], v[26:27], v[172:173] op_sel_hi:[1,0]
	v_pk_mul_f32 v[24:25], v[24:25], v[172:173] op_sel_hi:[1,0]
	v_pk_mul_f32 v[22:23], v[22:23], v[172:173] op_sel_hi:[1,0]
	v_pk_mul_f32 v[20:21], v[20:21], v[172:173] op_sel_hi:[1,0]
	v_pk_mul_f32 v[18:19], v[18:19], v[172:173] op_sel_hi:[1,0]
	v_pk_mul_f32 v[16:17], v[16:17], v[172:173] op_sel_hi:[1,0]
	v_mul_f32_e32 v143, v143, v172
	v_mov_b32_e32 v172, v173
	s_branch .LBB0_502

.LBB0_509:
	s_mov_b32 s39, s12
	s_mov_b32 s12, s38
	s_add_i32 s38, s38, 1
	s_cmp_lg_u32 s12, 2
	s_cselect_b32 s38, s38, 0
	s_mulk_i32 s39, 0x6800
	s_setprio 2
	v_add3_u32 v125, v166, s39, v164
	v_add_u32_e32 v134, 0x2000, v125
	v_add_u32_e32 v135, 0x3000, v125
	v_add_u32_e32 v180, 0x4000, v125
	v_add_u32_e32 v125, 0x5000, v125
	ds_read_b64 v[80:81], v134 offset:1024
	ds_read_b64 v[82:83], v134 offset:1040
	ds_read_b64 v[88:89], v135 offset:1280
	ds_read_b64 v[90:91], v135 offset:1296
	ds_read_b64 v[92:93], v180 offset:1536
	ds_read_b64 v[94:95], v180 offset:1552
	ds_read_b64 v[126:127], v125 offset:1792
	ds_read_b64 v[128:129], v125 offset:1808
	ds_read_b64 v[84:85], v134 offset:1056
	ds_read_b64 v[86:87], v134 offset:1072
	ds_read_b64 v[130:131], v135 offset:1312
	ds_read_b64 v[132:133], v135 offset:1328
	ds_read_b64 v[172:173], v180 offset:1568
	ds_read_b64 v[174:175], v180 offset:1584
	ds_read_b64 v[176:177], v125 offset:1824
	ds_read_b64 v[178:179], v125 offset:1840
	s_waitcnt lgkmcnt(14)
	v_mfma_f32_32x32x16_bf16 v[0:15], v[80:83], v[76:79], v[0:15]
	s_waitcnt lgkmcnt(12)
	v_mfma_f32_32x32x16_bf16 v[48:63], v[88:91], v[76:79], v[48:63]
	s_waitcnt lgkmcnt(10)
	v_mfma_f32_32x32x16_bf16 v[32:47], v[92:95], v[76:79], v[32:47]
	s_waitcnt lgkmcnt(8)
	v_mfma_f32_32x32x16_bf16 v[16:31], v[126:129], v[76:79], v[16:31]
	s_waitcnt lgkmcnt(6)
	v_mfma_f32_32x32x16_bf16 v[0:15], v[84:87], v[72:75], v[0:15]
	s_waitcnt lgkmcnt(4)
	v_mfma_f32_32x32x16_bf16 v[48:63], v[130:133], v[72:75], v[48:63]
	s_waitcnt lgkmcnt(2)
	v_mfma_f32_32x32x16_bf16 v[32:47], v[172:175], v[72:75], v[32:47]
	s_waitcnt lgkmcnt(0)
	v_mfma_f32_32x32x16_bf16 v[16:31], v[176:179], v[72:75], v[16:31]
	ds_read_b64 v[72:73], v134 offset:1088
	ds_read_b64 v[74:75], v134 offset:1104
	ds_read_b64 v[80:81], v135 offset:1344
	ds_read_b64 v[82:83], v135 offset:1360
	ds_read_b64 v[84:85], v180 offset:1600
	ds_read_b64 v[86:87], v180 offset:1616
	ds_read_b64 v[88:89], v125 offset:1856
	ds_read_b64 v[90:91], v125 offset:1872
	ds_read_b64 v[76:77], v134 offset:1120
	ds_read_b64 v[78:79], v134 offset:1136
	ds_read_b64 v[92:93], v135 offset:1376
	ds_read_b64 v[94:95], v135 offset:1392
	ds_read_b64 v[126:127], v180 offset:1632
	ds_read_b64 v[128:129], v180 offset:1648
	ds_read_b64 v[130:131], v125 offset:1888
	ds_read_b64 v[132:133], v125 offset:1904
	s_waitcnt lgkmcnt(14)
	v_mfma_f32_32x32x16_bf16 v[0:15], v[72:75], v[68:71], v[0:15]
	s_waitcnt lgkmcnt(12)
	v_mfma_f32_32x32x16_bf16 v[48:63], v[80:83], v[68:71], v[48:63]
	s_waitcnt lgkmcnt(10)
	v_mfma_f32_32x32x16_bf16 v[32:47], v[84:87], v[68:71], v[32:47]
	s_waitcnt lgkmcnt(8)
	v_mfma_f32_32x32x16_bf16 v[16:31], v[88:91], v[68:71], v[16:31]
	s_waitcnt lgkmcnt(6)
	v_mfma_f32_32x32x16_bf16 v[0:15], v[76:79], v[64:67], v[0:15]
	s_waitcnt lgkmcnt(4)
	v_mfma_f32_32x32x16_bf16 v[48:63], v[92:95], v[64:67], v[48:63]
	s_waitcnt lgkmcnt(2)
	v_mfma_f32_32x32x16_bf16 v[32:47], v[126:129], v[64:67], v[32:47]
	s_waitcnt lgkmcnt(0)
	v_mfma_f32_32x32x16_bf16 v[16:31], v[130:133], v[64:67], v[16:31]
	s_setprio 1
	s_mul_i32 s39, s38, 0x6800
	s_add_i32 s39, s39, 16
	v_add3_u32 v64, s39, v159, v160
	s_waitcnt vmcnt(1)
	ds_write_b128 v64, v[120:123]
	v_add_u32_e32 v64, s39, v161
	s_add_i32 s39, s13, 2
	s_min_i32 s39, s39, s6
	v_add_u32_e32 v65, 0x2400, v64
	v_add_u32_e32 v64, 0x4600, v64
	s_lshl_b32 s40, s39, 6
	s_waitcnt vmcnt(0)
	ds_write2_b64 v64, v[116:117], v[118:119] offset1:1
	v_add_u32_e32 v64, s40, v158
	ds_write2_b64 v65, v[112:113], v[114:115] offset1:1
	v_ashrrev_i32_e32 v65, 31, v64
	v_lshlrev_b64 v[64:65], 10, v[64:65]
	s_ashr_i32 s41, s40, 31
	v_lshl_add_u64 v[64:65], v[156:157], 0, v[64:65]
	s_lshl_b64 s[40:41], s[40:41], 1
	v_lshl_add_u64 v[66:67], v[152:153], 0, s[40:41]
	global_load_dwordx4 v[120:123], v[64:65], off
	v_lshl_add_u64 v[64:65], v[154:155], 0, s[40:41]
	global_load_dwordx4 v[112:115], v[66:67], off
	global_load_dwordx4 v[116:119], v[64:65], off
	s_mul_i32 s39, s12, 0x6800
	s_setprio 2
	v_add3_u32 v72, v165, s39, v163
	ds_read_b128 v[64:67], v72
	ds_read_b128 v[68:71], v72 offset:4608
	ds_read_b128 v[126:129], v72 offset:32
	ds_read_b128 v[130:133], v72 offset:4640
	ds_read_b128 v[172:175], v72 offset:64
	ds_read_b128 v[176:179], v72 offset:4672
	ds_read_b128 v[180:183], v72 offset:96
	ds_read_b128 v[184:187], v72 offset:4704
	s_waitcnt lgkmcnt(7)
	v_mfma_f32_32x32x16_bf16 v[80:95], v[64:67], v[108:111], 0
	s_waitcnt lgkmcnt(6)
	v_mfma_f32_32x32x16_bf16 v[64:79], v[68:71], v[108:111], 0
	s_waitcnt lgkmcnt(5)
	v_mfma_f32_32x32x16_bf16 v[80:95], v[126:129], v[96:99], v[80:95]
	s_waitcnt lgkmcnt(4)
	v_mfma_f32_32x32x16_bf16 v[64:79], v[130:133], v[96:99], v[64:79]
	s_waitcnt lgkmcnt(3)
	v_mfma_f32_32x32x16_bf16 v[80:95], v[172:175], v[100:103], v[80:95]
	s_waitcnt lgkmcnt(2)
	v_mfma_f32_32x32x16_bf16 v[64:79], v[176:179], v[100:103], v[64:79]
	s_waitcnt lgkmcnt(1)
	v_mfma_f32_32x32x16_bf16 v[80:95], v[180:183], v[104:107], v[80:95]
	s_waitcnt lgkmcnt(0)
	v_mfma_f32_32x32x16_bf16 v[64:79], v[184:187], v[104:107], v[64:79]
	s_setprio 1
	s_nop 8
	v_max_f32_e32 v125, v81, v81
	v_max_f32_e32 v126, v80, v80
	v_max_f32_e32 v125, v126, v125
	v_max3_f32 v125, v125, v82, v83
	v_max3_f32 v125, v125, v84, v85
	v_max3_f32 v125, v125, v86, v87
	v_max3_f32 v125, v125, v88, v89
	v_max3_f32 v125, v125, v90, v91
	v_max3_f32 v125, v125, v92, v93
	v_max3_f32 v125, v125, v94, v95
	v_max3_f32 v125, v125, v64, v65
	v_max3_f32 v125, v125, v66, v67
	v_max3_f32 v125, v125, v68, v69
	v_max3_f32 v125, v125, v70, v71
	v_max3_f32 v125, v125, v72, v73
	v_max3_f32 v125, v125, v74, v75
	v_max3_f32 v125, v125, v76, v77
	v_max3_f32 v125, v125, v78, v79
	v_mov_b32_e32 v126, v125
	s_nop 1
	v_permlane32_swap_b32_e32 v125, v126
	v_max_f32_e32 v126, v126, v126
	v_max_f32_e32 v125, v125, v125
	v_max_f32_e32 v125, v125, v126
	v_mul_f32_e32 v125, 0x3e38aa3b, v125
	v_add_f32_e32 v126, 0x41000000, v124
	v_cmp_gt_f32_e32 vcc, v125, v126
	s_cbranch_vccz .LBB0_508
	v_max_f32_e32 v125, v125, v125
	v_max_f32_e32 v126, v124, v124
	v_max_f32_e32 v125, v126, v125
	v_sub_f32_e32 v124, v124, v125
	v_exp_f32_e32 v124, v124
	s_nop 0
	v_pk_mul_f32 v[14:15], v[14:15], v[124:125] op_sel_hi:[1,0]
	v_pk_mul_f32 v[12:13], v[12:13], v[124:125] op_sel_hi:[1,0]
	v_pk_mul_f32 v[10:11], v[10:11], v[124:125] op_sel_hi:[1,0]
	v_pk_mul_f32 v[8:9], v[8:9], v[124:125] op_sel_hi:[1,0]
	v_pk_mul_f32 v[6:7], v[6:7], v[124:125] op_sel_hi:[1,0]
	v_pk_mul_f32 v[4:5], v[4:5], v[124:125] op_sel_hi:[1,0]
	v_pk_mul_f32 v[2:3], v[2:3], v[124:125] op_sel_hi:[1,0]
	v_pk_mul_f32 v[0:1], v[0:1], v[124:125] op_sel_hi:[1,0]
	v_pk_mul_f32 v[62:63], v[62:63], v[124:125] op_sel_hi:[1,0]
	v_pk_mul_f32 v[60:61], v[60:61], v[124:125] op_sel_hi:[1,0]
	v_pk_mul_f32 v[58:59], v[58:59], v[124:125] op_sel_hi:[1,0]
	v_pk_mul_f32 v[56:57], v[56:57], v[124:125] op_sel_hi:[1,0]
	v_pk_mul_f32 v[54:55], v[54:55], v[124:125] op_sel_hi:[1,0]
	v_pk_mul_f32 v[52:53], v[52:53], v[124:125] op_sel_hi:[1,0]
	v_pk_mul_f32 v[50:51], v[50:51], v[124:125] op_sel_hi:[1,0]
	v_pk_mul_f32 v[48:49], v[48:49], v[124:125] op_sel_hi:[1,0]
	v_pk_mul_f32 v[46:47], v[46:47], v[124:125] op_sel_hi:[1,0]
	v_pk_mul_f32 v[44:45], v[44:45], v[124:125] op_sel_hi:[1,0]
	v_pk_mul_f32 v[42:43], v[42:43], v[124:125] op_sel_hi:[1,0]
	v_pk_mul_f32 v[40:41], v[40:41], v[124:125] op_sel_hi:[1,0]
	v_pk_mul_f32 v[38:39], v[38:39], v[124:125] op_sel_hi:[1,0]
	v_pk_mul_f32 v[36:37], v[36:37], v[124:125] op_sel_hi:[1,0]
	v_pk_mul_f32 v[34:35], v[34:35], v[124:125] op_sel_hi:[1,0]
	v_pk_mul_f32 v[32:33], v[32:33], v[124:125] op_sel_hi:[1,0]
	v_pk_mul_f32 v[30:31], v[30:31], v[124:125] op_sel_hi:[1,0]
	v_pk_mul_f32 v[28:29], v[28:29], v[124:125] op_sel_hi:[1,0]
	v_pk_mul_f32 v[26:27], v[26:27], v[124:125] op_sel_hi:[1,0]
	v_pk_mul_f32 v[24:25], v[24:25], v[124:125] op_sel_hi:[1,0]
	v_pk_mul_f32 v[22:23], v[22:23], v[124:125] op_sel_hi:[1,0]
	v_pk_mul_f32 v[20:21], v[20:21], v[124:125] op_sel_hi:[1,0]
	v_pk_mul_f32 v[18:19], v[18:19], v[124:125] op_sel_hi:[1,0]
	v_pk_mul_f32 v[16:17], v[16:17], v[124:125] op_sel_hi:[1,0]
	v_mul_f32_e32 v143, v143, v124
	v_mov_b32_e32 v124, v125
	s_branch .LBB0_508
